# grid barrier: the first workgroup of each XCD to arrive issues an early L2 write-back so the leader's write-back has less to flush
# baseline (speedup 1.0000x reference)
; __device__ __forceinline__ unsigned xb_ld(unsigned* p)              { return __hip_atomic_load(p, __ATOMIC_RELAXED, __HIP_MEMORY_SCOPE_AGENT); }
; __device__ __forceinline__ unsigned xb_add(unsigned* p, unsigned v) { return __hip_atomic_fetch_add(p, v, __ATOMIC_RELAXED, __HIP_MEMORY_SCOPE_AGENT); }
; #define XB_SPIN(cond, bar) do { unsigned _sp = 0; while (cond) { __builtin_amdgcn_s_sleep(1); \
;     if ((++_sp & 255u) == 0u) { if (xb_ld(&(bar)[XB_TMO])) break; if (_sp > XB_SPIN_CAP) { atomicAdd(&(bar)[XB_TMO], 1u); break; } } } } while (0)
; __device__ __forceinline__ void xcd_barrier(const XcdBarrier& b) {
;     ...
;         const unsigned old = xb_add(&bar[XB_XSUB(b.x)], 1u);
;         const unsigned gen = old / nloc;
;         if (old + 1u == (gen + 1u) * nloc) {
;             __builtin_amdgcn_fence(__ATOMIC_RELEASE, "agent");
;             asm volatile("s_waitcnt vmcnt(0)" ::: "memory");
;             const unsigned og = xb_add(&bar[XB_TOP], 1u);
;             const unsigned tg = og / nx;
;             if (og + 1u == (tg + 1u) * nx) xb_add(&bar[XB_TOPGEN], 1u);
;             else XB_SPIN(xb_ld(&bar[XB_TOPGEN]) == tg, bar);
;             __builtin_amdgcn_fence(__ATOMIC_ACQUIRE, "agent");
;             xb_add(&bar[XB_XGEN(b.x)], 1u);
;             asm volatile("s_waitcnt vmcnt(0)" ::: "memory");
;         } else {
;             XB_SPIN(xb_ld(&bar[XB_XGEN(b.x)]) == gen, bar);
.LBB0_148:
	global_atomic_add v3, v[130:131], v176, off sc0
	v_cvt_f32_u32_e32 v1, v2
	v_sub_u32_e32 v4, 0, v2
	v_rcp_iflag_f32_e32 v1, v1
	s_nop 0
	v_mul_f32_e32 v1, 0x4f7ffffe, v1
	v_cvt_u32_f32_e32 v1, v1
	v_mul_lo_u32 v4, v4, v1
	v_mul_hi_u32 v4, v1, v4
	v_add_u32_e32 v1, v1, v4
	s_waitcnt vmcnt(0)
	v_mul_hi_u32 v1, v3, v1
	v_mul_lo_u32 v4, v1, v2
	v_sub_u32_e32 v4, v3, v4
	v_add_u32_e32 v5, 1, v1
	v_sub_u32_e32 v6, v4, v2
	v_cmp_ge_u32_e32 vcc, v4, v2
	v_add_u32_e32 v3, 1, v3
	s_nop 0
	v_cndmask_b32_e32 v1, v1, v5, vcc
	v_cndmask_b32_e32 v4, v4, v6, vcc
	v_add_u32_e32 v5, 1, v1
	v_cmp_ge_u32_e32 vcc, v4, v2
	s_nop 1
	v_cndmask_b32_e32 v1, v1, v5, vcc
	v_mul_lo_u32 v4, v2, v1
	v_add_u32_e32 v2, v4, v2
	v_cmp_ne_u32_e32 vcc, v3, v2
	s_and_saveexec_b64 s[6:7], vcc
	s_xor_b64 s[38:39], exec, s[6:7]
	s_cbranch_execz .LBB0_162
	v_add_u32_e32 v5, 1, v4
	v_cmp_eq_u32_e32 vcc, v3, v5
	s_cbranch_vccz .Lpc0
	buffer_wbl2 sc1
.Lpc0:
	s_waitcnt lgkmcnt(0)
	buffer_inv sc1
	global_load_dword v0, v[132:133], off sc1
	s_waitcnt vmcnt(0)
	v_cmp_eq_u32_e32 vcc, v0, v1
	s_and_saveexec_b64 s[40:41], vcc
	s_cbranch_execz .LBB0_161
	s_mov_b32 s2, 1
	s_mov_b64 s[42:43], 0
	s_branch .LBB0_152

; __device__ __forceinline__ unsigned xb_ld(unsigned* p)              { return __hip_atomic_load(p, __ATOMIC_RELAXED, __HIP_MEMORY_SCOPE_AGENT); }
; __device__ __forceinline__ unsigned xb_add(unsigned* p, unsigned v) { return __hip_atomic_fetch_add(p, v, __ATOMIC_RELAXED, __HIP_MEMORY_SCOPE_AGENT); }
; #define XB_SPIN(cond, bar) do { unsigned _sp = 0; while (cond) { __builtin_amdgcn_s_sleep(1); \
;     if ((++_sp & 255u) == 0u) { if (xb_ld(&(bar)[XB_TMO])) break; if (_sp > XB_SPIN_CAP) { atomicAdd(&(bar)[XB_TMO], 1u); break; } } } } while (0)
; __device__ __forceinline__ void xcd_barrier(const XcdBarrier& b) {
;     ...
;         const unsigned old = xb_add(&bar[XB_XSUB(b.x)], 1u);
;         const unsigned gen = old / nloc;
;         if (old + 1u == (gen + 1u) * nloc) {
;             __builtin_amdgcn_fence(__ATOMIC_RELEASE, "agent");
;             asm volatile("s_waitcnt vmcnt(0)" ::: "memory");
;             const unsigned og = xb_add(&bar[XB_TOP], 1u);
;             const unsigned tg = og / nx;
;             if (og + 1u == (tg + 1u) * nx) xb_add(&bar[XB_TOPGEN], 1u);
;             else XB_SPIN(xb_ld(&bar[XB_TOPGEN]) == tg, bar);
;             __builtin_amdgcn_fence(__ATOMIC_ACQUIRE, "agent");
;             xb_add(&bar[XB_XGEN(b.x)], 1u);
;             asm volatile("s_waitcnt vmcnt(0)" ::: "memory");
;         } else {
;             XB_SPIN(xb_ld(&bar[XB_XGEN(b.x)]) == gen, bar);
.LBB0_208:
	global_atomic_add v3, v[130:131], v176, off sc0
	v_cvt_f32_u32_e32 v1, v2
	v_sub_u32_e32 v4, 0, v2
	v_rcp_iflag_f32_e32 v1, v1
	s_nop 0
	v_mul_f32_e32 v1, 0x4f7ffffe, v1
	v_cvt_u32_f32_e32 v1, v1
	v_mul_lo_u32 v4, v4, v1
	v_mul_hi_u32 v4, v1, v4
	v_add_u32_e32 v1, v1, v4
	s_waitcnt vmcnt(0)
	v_mul_hi_u32 v1, v3, v1
	v_mul_lo_u32 v4, v1, v2
	v_sub_u32_e32 v4, v3, v4
	v_add_u32_e32 v5, 1, v1
	v_cmp_ge_u32_e32 vcc, v4, v2
	v_add_u32_e32 v3, 1, v3
	s_nop 0
	v_cndmask_b32_e32 v1, v1, v5, vcc
	v_sub_u32_e32 v5, v4, v2
	v_cndmask_b32_e32 v4, v4, v5, vcc
	v_add_u32_e32 v5, 1, v1
	v_cmp_ge_u32_e32 vcc, v4, v2
	s_nop 1
	v_cndmask_b32_e32 v1, v1, v5, vcc
	v_mul_lo_u32 v4, v2, v1
	v_add_u32_e32 v2, v4, v2
	v_cmp_ne_u32_e32 vcc, v3, v2
	s_and_saveexec_b64 s[6:7], vcc
	s_xor_b64 s[38:39], exec, s[6:7]
	s_cbranch_execz .LBB0_222
	v_add_u32_e32 v5, 1, v4
	v_cmp_eq_u32_e32 vcc, v3, v5
	s_cbranch_vccz .Lpc2
	buffer_wbl2 sc1

; __device__ __forceinline__ unsigned xb_ld(unsigned* p)              { return __hip_atomic_load(p, __ATOMIC_RELAXED, __HIP_MEMORY_SCOPE_AGENT); }
; #define XB_SPIN(cond, bar) do { unsigned _sp = 0; while (cond) { __builtin_amdgcn_s_sleep(1); \
;     if ((++_sp & 255u) == 0u) { if (xb_ld(&(bar)[XB_TMO])) break; if (_sp > XB_SPIN_CAP) { atomicAdd(&(bar)[XB_TMO], 1u); break; } } } } while (0)
; __device__ __forceinline__ void xcd_barrier(const XcdBarrier& b) {
;     ...
;             XB_SPIN(xb_ld(&bar[XB_XGEN(b.x)]) == gen, bar);
;             __builtin_amdgcn_fence(__ATOMIC_ACQUIRE, "agent");
;             asm volatile("s_waitcnt vmcnt(0)" ::: "memory");
.Lpc10:
	s_waitcnt lgkmcnt(0)
	buffer_inv sc1
	global_load_dword v0, v[132:133], off sc1
	s_waitcnt vmcnt(0)
	v_cmp_eq_u32_e32 vcc, v0, v1
	s_and_saveexec_b64 s[40:41], vcc
	s_cbranch_execz .LBB0_549
	s_mov_b32 s6, 1
	s_mov_b64 s[42:43], 0
	s_branch .LBB0_540
